# out-projection GEMM epilogue: residual loads of round k+1 issued one round early into a spare register buffer and copied into place (on top of the hand-written final LayerNorm pass)
# speedup vs baseline: 1.0049x; 1.0049x over previous
.LBB0_583:
	v_lshl_add_u32 v156, s56, 8, v170
	v_lshl_or_b32 v154, s54, 8, v181
	v_ashrrev_i32_e32 v155, 31, v154
	v_ashrrev_i32_e32 v157, 31, v156
	v_lshl_add_u64 v[158:159], v[154:155], 2, s[4:5]
	v_lshlrev_b64 v[128:129], 12, v[156:157]
	v_or_b32_e32 v168, 16, v156
	v_lshl_add_u64 v[128:129], v[158:159], 0, v[128:129]
	v_ashrrev_i32_e32 v169, 31, v168
	global_load_dwordx4 v[186:189], v[128:129], off offset:16
	global_load_dwordx4 v[190:193], v[128:129], off
	global_load_dwordx4 v[194:197], v[128:129], off offset:528
	global_load_dwordx4 v[202:205], v[128:129], off offset:512
	v_lshlrev_b64 v[128:129], 12, v[168:169]
	v_lshl_add_u64 v[132:133], v[158:159], 0, v[128:129]
	global_load_dwordx4 v[136:139], v[132:133], off offset:16
	global_load_dwordx4 v[140:143], v[132:133], off
	global_load_dwordx4 v[128:131], v[132:133], off offset:528
	s_nop 0
	global_load_dwordx4 v[132:135], v[132:133], off offset:512
	v_add_u32_e32 v248, 0x20, v156
	v_ashrrev_i32_e32 v249, 31, v248
	v_lshlrev_b64 v[248:249], 12, v[248:249]
	v_lshl_add_u64 v[248:249], v[158:159], 0, v[248:249]
	global_load_dwordx4 v[214:217], v[248:249], off offset:16
	global_load_dwordx4 v[218:221], v[248:249], off
	global_load_dwordx4 v[222:225], v[248:249], off offset:528
	global_load_dwordx4 v[226:229], v[248:249], off offset:512
	v_add_u32_e32 v250, 0x30, v156
	v_ashrrev_i32_e32 v251, 31, v250
	v_lshlrev_b64 v[250:251], 12, v[250:251]
	v_lshl_add_u64 v[250:251], v[158:159], 0, v[250:251]
	global_load_dwordx4 v[230:233], v[250:251], off offset:16
	global_load_dwordx4 v[234:237], v[250:251], off
	global_load_dwordx4 v[238:241], v[250:251], off offset:528
	global_load_dwordx4 v[242:245], v[250:251], off offset:512
	s_lshl_b32 s30, s54, 2
	s_ashr_i32 s31, s30, 31
	s_or_b64 s[54:55], s[30:31], s[14:15]
	v_lshlrev_b64 v[198:199], 11, v[156:157]
	s_waitcnt vmcnt(8)
	v_pk_fma_f32 v[124:125], v[190:191], s[44:45], v[124:125] op_sel_hi:[1,0,1]
	v_lshl_add_u64 v[190:191], s[28:29], 0, v[198:199]
	v_lshl_add_u64 v[190:191], v[154:155], 1, v[190:191]
	v_pk_fma_f32 v[126:127], v[192:193], s[44:45], v[126:127] op_sel_hi:[1,0,1]
	v_pk_fma_f32 v[188:189], v[188:189], s[44:45], v[122:123] op_sel_hi:[1,0,1]
	v_pk_fma_f32 v[186:187], v[186:187], s[44:45], v[120:121] op_sel_hi:[1,0,1]
	v_cvt_pk_bf16_f32 v120, v124, v125
	v_cvt_pk_bf16_f32 v121, v126, v127
	v_pk_fma_f32 v[118:119], v[204:205], s[44:45], v[118:119] op_sel_hi:[1,0,1]
	v_cvt_pk_bf16_f32 v122, v186, v187
	v_cvt_pk_bf16_f32 v123, v188, v189
	global_store_dwordx4 v[190:191], v[120:123], off
	v_pk_fma_f32 v[202:203], v[202:203], s[44:45], v[116:117] op_sel_hi:[1,0,1]
	v_pk_fma_f32 v[196:197], v[196:197], s[44:45], v[114:115] op_sel_hi:[1,0,1]
	v_pk_fma_f32 v[194:195], v[194:195], s[44:45], v[112:113] op_sel_hi:[1,0,1]
	v_cvt_pk_bf16_f32 v112, v202, v203
	v_cvt_pk_bf16_f32 v113, v118, v119
	v_add_f32_e32 v120, v124, v125
	v_cvt_pk_bf16_f32 v114, v194, v195
	v_cvt_pk_bf16_f32 v115, v196, v197
	global_store_dwordx4 v[190:191], v[112:115], off offset:256
	v_add_f32_e32 v122, v126, v127
	v_mul_f32_e32 v207, v124, v124
	v_pk_mul_f32 v[112:113], v[196:197], v[196:197]
	v_pk_mul_f32 v[114:115], v[194:195], v[194:195]
	v_mul_f32_e32 v125, v125, v125
	v_pk_mov_b32 v[116:117], v[114:115], v[112:113] op_sel:[1,0]
	v_mov_b32_e32 v115, v113
	v_mul_f32_e32 v209, v126, v126
	v_mul_f32_e32 v127, v127, v127
	v_pk_add_f32 v[112:113], v[116:117], v[114:115]
	v_and_b32_e32 v114, 64, v185
	v_mov_b32_e32 v206, v202
	v_mov_b32_e32 v124, v203
	v_mov_b32_e32 v208, v118
	v_mov_b32_e32 v126, v119
	v_add_f32_e32 v192, v186, v187
	v_add_f32_e32 v198, v188, v189
	v_mul_f32_e32 v211, v186, v186
	v_mul_f32_e32 v187, v187, v187
	v_mul_f32_e32 v213, v188, v188
	v_mul_f32_e32 v189, v189, v189
	v_mul_f32_e32 v193, v118, v118
	v_mul_f32_e32 v199, v119, v119
	v_add_u32_e32 v117, 64, v114
	v_pk_add_f32 v[114:115], v[206:207], v[124:125]
	v_pk_add_f32 v[118:119], v[208:209], v[126:127]
	v_mov_b32_e32 v210, v194
	v_mov_b32_e32 v186, v195
	v_mov_b32_e32 v212, v196
	v_mov_b32_e32 v188, v197
	v_pk_add_f32 v[112:113], v[112:113], v[112:113] op_sel_hi:[0,1]
	v_pk_add_f32 v[114:115], v[114:115], v[118:119]
	v_pk_add_f32 v[118:119], v[210:211], v[186:187]
	v_pk_add_f32 v[124:125], v[212:213], v[188:189]
	v_mul_f32_e32 v121, v202, v202
	v_mul_f32_e32 v123, v203, v203
	v_xor_b32_e32 v112, 16, v185
	v_pk_add_f32 v[118:119], v[118:119], v[124:125]
	v_cmp_lt_i32_e32 vcc, v112, v117
	v_pk_add_f32 v[114:115], v[114:115], v[118:119]
	v_pk_add_f32 v[118:119], v[120:121], v[122:123]
	v_pk_add_f32 v[120:121], v[192:193], v[198:199]
	v_cndmask_b32_e32 v112, v185, v112, vcc
	v_pk_add_f32 v[118:119], v[118:119], v[120:121]
	v_mov_b32_e32 v147, v113
	v_lshlrev_b32_e32 v116, 2, v112
	v_pk_add_f32 v[112:113], v[118:119], v[146:147]
	s_nop 0
	v_pk_add_f32 v[112:113], v[114:115], v[112:113]
	ds_bpermute_b32 v114, v116, v112
	ds_bpermute_b32 v115, v116, v113
	s_waitcnt lgkmcnt(0)
	v_pk_add_f32 v[112:113], v[112:113], v[114:115]
	v_xor_b32_e32 v114, 32, v185
	v_cmp_lt_i32_e32 vcc, v114, v117
	s_nop 1
	v_cndmask_b32_e32 v114, v185, v114, vcc
	v_lshlrev_b32_e32 v117, 2, v114
	ds_bpermute_b32 v114, v117, v112
	ds_bpermute_b32 v115, v117, v113
	s_and_saveexec_b64 s[56:57], s[38:39]
	s_cbranch_execz .LBB0_585
	v_lshlrev_b64 v[118:119], 7, v[156:157]
	s_waitcnt lgkmcnt(0)
	v_pk_add_f32 v[112:113], v[112:113], v[114:115]
	v_lshl_add_u64 v[114:115], s[12:13], 0, v[118:119]
	v_lshl_add_u64 v[114:115], s[54:55], 3, v[114:115]
	global_store_dwordx2 v[114:115], v[112:113], off

.LBB0_587:
	s_or_b64 exec, exec, s[56:57]
	v_or_b32_e32 v114, 32, v156
	v_ashrrev_i32_e32 v115, 31, v114
	v_lshlrev_b64 v[96:97], 12, v[114:115]
	v_or_b32_e32 v112, 48, v156
	v_lshl_add_u64 v[96:97], v[158:159], 0, v[96:97]
	v_ashrrev_i32_e32 v113, 31, v112
	s_waitcnt vmcnt(4)
	v_mov_b32_e32 v118, v214
	v_mov_b32_e32 v119, v215
	v_mov_b32_e32 v120, v216
	v_mov_b32_e32 v121, v217
	v_mov_b32_e32 v122, v218
	v_mov_b32_e32 v123, v219
	v_mov_b32_e32 v124, v220
	v_mov_b32_e32 v125, v221
	v_mov_b32_e32 v126, v222
	v_mov_b32_e32 v127, v223
	v_mov_b32_e32 v128, v224
	v_mov_b32_e32 v129, v225
	v_mov_b32_e32 v130, v226
	v_mov_b32_e32 v131, v227
	v_mov_b32_e32 v132, v228
	v_mov_b32_e32 v133, v229
	v_lshlrev_b64 v[96:97], 12, v[112:113]
	v_lshl_add_u64 v[100:101], v[158:159], 0, v[96:97]
	v_mov_b32_e32 v104, v230
	v_mov_b32_e32 v105, v231
	v_mov_b32_e32 v106, v232
	v_mov_b32_e32 v107, v233
	v_mov_b32_e32 v108, v234
	v_mov_b32_e32 v109, v235
	v_mov_b32_e32 v110, v236
	v_mov_b32_e32 v111, v237
	s_waitcnt lgkmcnt(0)
	v_mov_b32_e32 v96, v238
	v_mov_b32_e32 v97, v239
	v_mov_b32_e32 v98, v240
	v_mov_b32_e32 v99, v241
	s_nop 0
	v_mov_b32_e32 v100, v242
	v_mov_b32_e32 v101, v243
	v_mov_b32_e32 v102, v244
	v_mov_b32_e32 v103, v245
	v_add_u32_e32 v248, 0x80, v156
	v_ashrrev_i32_e32 v249, 31, v248
	v_lshlrev_b64 v[248:249], 12, v[248:249]
	v_lshl_add_u64 v[248:249], v[158:159], 0, v[248:249]
	global_load_dwordx4 v[214:217], v[248:249], off offset:16
	global_load_dwordx4 v[218:221], v[248:249], off
	global_load_dwordx4 v[222:225], v[248:249], off offset:528
	global_load_dwordx4 v[226:229], v[248:249], off offset:512
	v_add_u32_e32 v250, 0x90, v156
	v_ashrrev_i32_e32 v251, 31, v250
	v_lshlrev_b64 v[250:251], 12, v[250:251]
	v_lshl_add_u64 v[250:251], v[158:159], 0, v[250:251]
	global_load_dwordx4 v[230:233], v[250:251], off offset:16
	global_load_dwordx4 v[234:237], v[250:251], off
	global_load_dwordx4 v[238:241], v[250:251], off offset:528
	global_load_dwordx4 v[242:245], v[250:251], off offset:512
	v_lshlrev_b64 v[134:135], 11, v[114:115]
	v_pk_fma_f32 v[92:93], v[122:123], s[44:45], v[92:93] op_sel_hi:[1,0,1]
	v_lshl_add_u64 v[122:123], s[28:29], 0, v[134:135]
	v_lshl_add_u64 v[122:123], v[154:155], 1, v[122:123]
	v_pk_fma_f32 v[94:95], v[124:125], s[44:45], v[94:95] op_sel_hi:[1,0,1]
	v_pk_fma_f32 v[120:121], v[120:121], s[44:45], v[90:91] op_sel_hi:[1,0,1]
	v_pk_fma_f32 v[118:119], v[118:119], s[44:45], v[88:89] op_sel_hi:[1,0,1]
	v_cvt_pk_bf16_f32 v88, v92, v93
	v_cvt_pk_bf16_f32 v89, v94, v95
	v_pk_fma_f32 v[86:87], v[132:133], s[44:45], v[86:87] op_sel_hi:[1,0,1]
	v_cvt_pk_bf16_f32 v90, v118, v119
	v_cvt_pk_bf16_f32 v91, v120, v121
	global_store_dwordx4 v[122:123], v[88:91], off
	v_pk_fma_f32 v[84:85], v[130:131], s[44:45], v[84:85] op_sel_hi:[1,0,1]
	v_pk_fma_f32 v[128:129], v[128:129], s[44:45], v[82:83] op_sel_hi:[1,0,1]
	v_pk_fma_f32 v[126:127], v[126:127], s[44:45], v[80:81] op_sel_hi:[1,0,1]
	v_cvt_pk_bf16_f32 v80, v84, v85
	v_cvt_pk_bf16_f32 v81, v86, v87
	v_add_f32_e32 v88, v92, v93
	v_cvt_pk_bf16_f32 v82, v126, v127
	v_cvt_pk_bf16_f32 v83, v128, v129
	global_store_dwordx4 v[122:123], v[80:83], off offset:256
	v_add_f32_e32 v90, v94, v95
	v_mul_f32_e32 v137, v92, v92
	v_pk_mul_f32 v[80:81], v[128:129], v[128:129]
	v_pk_mul_f32 v[82:83], v[126:127], v[126:127]
	v_mul_f32_e32 v93, v93, v93
	v_mul_f32_e32 v139, v94, v94
	v_mul_f32_e32 v95, v95, v95
	v_pk_mov_b32 v[122:123], v[82:83], v[80:81] op_sel:[1,0]
	v_mov_b32_e32 v83, v81
	v_mov_b32_e32 v136, v84
	v_mov_b32_e32 v92, v85
	v_mov_b32_e32 v138, v86
	v_mov_b32_e32 v94, v87
	v_add_f32_e32 v124, v118, v119
	v_add_f32_e32 v134, v120, v121
	v_mul_f32_e32 v141, v118, v118
	v_mul_f32_e32 v119, v119, v119
	v_mul_f32_e32 v143, v120, v120
	v_mul_f32_e32 v121, v121, v121
	v_mul_f32_e32 v89, v84, v84
	v_mul_f32_e32 v91, v85, v85
	v_pk_add_f32 v[80:81], v[122:123], v[82:83]
	v_pk_add_f32 v[82:83], v[136:137], v[92:93]
	v_pk_add_f32 v[84:85], v[138:139], v[94:95]
	v_mov_b32_e32 v140, v126
	v_mov_b32_e32 v118, v127
	v_mov_b32_e32 v142, v128
	v_mov_b32_e32 v120, v129
	v_mul_f32_e32 v125, v86, v86
	v_mul_f32_e32 v135, v87, v87
	v_pk_add_f32 v[82:83], v[82:83], v[84:85]
	v_pk_add_f32 v[84:85], v[140:141], v[118:119]
	v_pk_add_f32 v[86:87], v[142:143], v[120:121]
	v_pk_add_f32 v[80:81], v[80:81], v[80:81] op_sel_hi:[0,1]
	v_pk_add_f32 v[84:85], v[84:85], v[86:87]
	v_pk_add_f32 v[86:87], v[124:125], v[134:135]
	v_pk_add_f32 v[82:83], v[82:83], v[84:85]
	v_pk_add_f32 v[84:85], v[88:89], v[90:91]
	v_mov_b32_e32 v147, v81
	v_pk_add_f32 v[84:85], v[84:85], v[86:87]
	s_nop 0
	v_pk_add_f32 v[80:81], v[84:85], v[146:147]
	s_nop 0
	v_pk_add_f32 v[80:81], v[82:83], v[80:81]
	ds_bpermute_b32 v82, v116, v80
	ds_bpermute_b32 v83, v116, v81
	s_waitcnt lgkmcnt(0)
	v_pk_add_f32 v[80:81], v[80:81], v[82:83]
	ds_bpermute_b32 v82, v117, v80
	ds_bpermute_b32 v83, v117, v81
	s_and_saveexec_b64 s[56:57], s[38:39]
	s_cbranch_execz .LBB0_589
	v_lshlrev_b64 v[84:85], 7, v[114:115]
	s_waitcnt lgkmcnt(0)
	v_pk_add_f32 v[80:81], v[80:81], v[82:83]
	v_lshl_add_u64 v[82:83], s[12:13], 0, v[84:85]
	v_lshl_add_u64 v[82:83], s[54:55], 3, v[82:83]
	global_store_dwordx2 v[82:83], v[80:81], off
.LBB0_589:
	s_or_b64 exec, exec, s[56:57]
	v_lshlrev_b64 v[80:81], 11, v[112:113]
	v_lshl_add_u64 v[80:81], s[28:29], 0, v[80:81]
	v_lshl_add_u64 v[80:81], v[154:155], 1, v[80:81]
	v_pk_fma_f32 v[78:79], v[110:111], s[44:45], v[78:79] op_sel_hi:[1,0,1]
	v_pk_fma_f32 v[76:77], v[108:109], s[44:45], v[76:77] op_sel_hi:[1,0,1]
	s_waitcnt lgkmcnt(0)
	v_pk_fma_f32 v[82:83], v[106:107], s[44:45], v[74:75] op_sel_hi:[1,0,1]
	v_pk_fma_f32 v[84:85], v[104:105], s[44:45], v[72:73] op_sel_hi:[1,0,1]
	v_cvt_pk_bf16_f32 v72, v76, v77
	v_cvt_pk_bf16_f32 v73, v78, v79
	v_pk_fma_f32 v[70:71], v[102:103], s[44:45], v[70:71] op_sel_hi:[1,0,1]
	v_cvt_pk_bf16_f32 v74, v84, v85
	v_cvt_pk_bf16_f32 v75, v82, v83
	global_store_dwordx4 v[80:81], v[72:75], off
	v_pk_fma_f32 v[68:69], v[100:101], s[44:45], v[68:69] op_sel_hi:[1,0,1]
	v_pk_fma_f32 v[98:99], v[98:99], s[44:45], v[66:67] op_sel_hi:[1,0,1]
	v_pk_fma_f32 v[96:97], v[96:97], s[44:45], v[64:65] op_sel_hi:[1,0,1]
	v_cvt_pk_bf16_f32 v64, v68, v69
	v_cvt_pk_bf16_f32 v65, v70, v71
	v_add_f32_e32 v72, v76, v77
	v_cvt_pk_bf16_f32 v66, v96, v97
	v_cvt_pk_bf16_f32 v67, v98, v99
	global_store_dwordx4 v[80:81], v[64:67], off offset:256
	v_add_f32_e32 v74, v78, v79
	v_mul_f32_e32 v91, v76, v76
	v_pk_mul_f32 v[64:65], v[98:99], v[98:99]
	v_pk_mul_f32 v[66:67], v[96:97], v[96:97]
	v_mul_f32_e32 v77, v77, v77
	v_mul_f32_e32 v93, v78, v78
	v_mul_f32_e32 v79, v79, v79
	v_pk_mov_b32 v[80:81], v[66:67], v[64:65] op_sel:[1,0]
	v_mov_b32_e32 v67, v65
	v_mov_b32_e32 v90, v68
	v_mov_b32_e32 v76, v69
	v_mov_b32_e32 v92, v70
	v_mov_b32_e32 v78, v71
	v_add_f32_e32 v86, v84, v85
	v_add_f32_e32 v88, v82, v83
	v_mul_f32_e32 v95, v84, v84
	v_mul_f32_e32 v85, v85, v85
	v_mul_f32_e32 v105, v82, v82
	v_mul_f32_e32 v83, v83, v83
	v_mul_f32_e32 v73, v68, v68
	v_mul_f32_e32 v75, v69, v69
	v_pk_add_f32 v[64:65], v[80:81], v[66:67]
	v_pk_add_f32 v[66:67], v[90:91], v[76:77]
	v_pk_add_f32 v[68:69], v[92:93], v[78:79]
	v_mov_b32_e32 v94, v96
	v_mov_b32_e32 v84, v97
	v_mov_b32_e32 v104, v98
	v_mov_b32_e32 v82, v99
	v_mul_f32_e32 v87, v70, v70
	v_mul_f32_e32 v89, v71, v71
	v_pk_add_f32 v[66:67], v[66:67], v[68:69]
	v_pk_add_f32 v[68:69], v[94:95], v[84:85]
	v_pk_add_f32 v[70:71], v[104:105], v[82:83]
	v_pk_add_f32 v[64:65], v[64:65], v[64:65] op_sel_hi:[0,1]
	v_pk_add_f32 v[68:69], v[68:69], v[70:71]
	v_pk_add_f32 v[70:71], v[86:87], v[88:89]
	v_pk_add_f32 v[66:67], v[66:67], v[68:69]
	v_pk_add_f32 v[68:69], v[72:73], v[74:75]
	v_mov_b32_e32 v147, v65
	v_pk_add_f32 v[68:69], v[68:69], v[70:71]
	s_nop 0
	v_pk_add_f32 v[64:65], v[68:69], v[146:147]
	s_nop 0
	v_pk_add_f32 v[64:65], v[66:67], v[64:65]
	ds_bpermute_b32 v66, v116, v64
	ds_bpermute_b32 v67, v116, v65
	s_waitcnt lgkmcnt(0)
	v_pk_add_f32 v[64:65], v[64:65], v[66:67]
	ds_bpermute_b32 v66, v117, v64
	ds_bpermute_b32 v67, v117, v65
	s_and_saveexec_b64 s[56:57], s[38:39]
	s_cbranch_execz .LBB0_591
	v_lshlrev_b64 v[68:69], 7, v[112:113]
	s_waitcnt lgkmcnt(0)
	v_pk_add_f32 v[64:65], v[64:65], v[66:67]
	v_lshl_add_u64 v[66:67], s[12:13], 0, v[68:69]
	v_lshl_add_u64 v[66:67], s[54:55], 3, v[66:67]
	global_store_dwordx2 v[66:67], v[64:65], off
.LBB0_591:
	s_or_b64 exec, exec, s[56:57]
	v_add_u32_e32 v82, 0x80, v156
	v_ashrrev_i32_e32 v83, 31, v82
	v_lshlrev_b64 v[64:65], 12, v[82:83]
	v_add_u32_e32 v80, 0x90, v156
	v_lshl_add_u64 v[64:65], v[158:159], 0, v[64:65]
	v_ashrrev_i32_e32 v81, 31, v80
	s_waitcnt vmcnt(4)
	v_mov_b32_e32 v84, v214
	v_mov_b32_e32 v85, v215
	v_mov_b32_e32 v86, v216
	v_mov_b32_e32 v87, v217
	v_mov_b32_e32 v88, v218
	v_mov_b32_e32 v89, v219
	v_mov_b32_e32 v90, v220
	v_mov_b32_e32 v91, v221
	v_mov_b32_e32 v92, v222
	v_mov_b32_e32 v93, v223
	v_mov_b32_e32 v94, v224
	v_mov_b32_e32 v95, v225
	v_mov_b32_e32 v96, v226
	v_mov_b32_e32 v97, v227
	v_mov_b32_e32 v98, v228
	v_mov_b32_e32 v99, v229
	v_lshlrev_b64 v[64:65], 12, v[80:81]
	v_lshl_add_u64 v[68:69], v[158:159], 0, v[64:65]
	v_mov_b32_e32 v72, v230
	v_mov_b32_e32 v73, v231
	v_mov_b32_e32 v74, v232
	v_mov_b32_e32 v75, v233
	v_mov_b32_e32 v76, v234
	v_mov_b32_e32 v77, v235
	v_mov_b32_e32 v78, v236
	v_mov_b32_e32 v79, v237
	s_waitcnt lgkmcnt(0)
	v_mov_b32_e32 v64, v238
	v_mov_b32_e32 v65, v239
	v_mov_b32_e32 v66, v240
	v_mov_b32_e32 v67, v241
	s_nop 0
	v_mov_b32_e32 v68, v242
	v_mov_b32_e32 v69, v243
	v_mov_b32_e32 v70, v244
	v_mov_b32_e32 v71, v245
	v_add_u32_e32 v248, 0xa0, v156
	v_ashrrev_i32_e32 v249, 31, v248
	v_lshlrev_b64 v[248:249], 12, v[248:249]
	v_lshl_add_u64 v[248:249], v[158:159], 0, v[248:249]
	global_load_dwordx4 v[214:217], v[248:249], off offset:16
	global_load_dwordx4 v[218:221], v[248:249], off
	global_load_dwordx4 v[222:225], v[248:249], off offset:528
	global_load_dwordx4 v[226:229], v[248:249], off offset:512
	v_add_u32_e32 v250, 0xb0, v156
	v_ashrrev_i32_e32 v251, 31, v250
	v_lshlrev_b64 v[250:251], 12, v[250:251]
	v_lshl_add_u64 v[250:251], v[158:159], 0, v[250:251]
	global_load_dwordx4 v[230:233], v[250:251], off offset:16
	global_load_dwordx4 v[234:237], v[250:251], off
	global_load_dwordx4 v[238:241], v[250:251], off offset:528
	global_load_dwordx4 v[242:245], v[250:251], off offset:512
	v_lshlrev_b64 v[100:101], 11, v[82:83]
	v_pk_fma_f32 v[60:61], v[88:89], s[44:45], v[60:61] op_sel_hi:[1,0,1]
	v_lshl_add_u64 v[88:89], s[28:29], 0, v[100:101]
	v_lshl_add_u64 v[88:89], v[154:155], 1, v[88:89]
	v_pk_fma_f32 v[62:63], v[90:91], s[44:45], v[62:63] op_sel_hi:[1,0,1]
	v_pk_fma_f32 v[86:87], v[86:87], s[44:45], v[58:59] op_sel_hi:[1,0,1]
	v_pk_fma_f32 v[84:85], v[84:85], s[44:45], v[56:57] op_sel_hi:[1,0,1]
	v_cvt_pk_bf16_f32 v56, v60, v61
	v_cvt_pk_bf16_f32 v57, v62, v63
	v_pk_fma_f32 v[54:55], v[98:99], s[44:45], v[54:55] op_sel_hi:[1,0,1]
	v_cvt_pk_bf16_f32 v58, v84, v85
	v_cvt_pk_bf16_f32 v59, v86, v87
	global_store_dwordx4 v[88:89], v[56:59], off
	v_pk_fma_f32 v[52:53], v[96:97], s[44:45], v[52:53] op_sel_hi:[1,0,1]
	v_pk_fma_f32 v[94:95], v[94:95], s[44:45], v[50:51] op_sel_hi:[1,0,1]
	v_pk_fma_f32 v[92:93], v[92:93], s[44:45], v[48:49] op_sel_hi:[1,0,1]
	v_cvt_pk_bf16_f32 v48, v52, v53
	v_cvt_pk_bf16_f32 v49, v54, v55
	v_add_f32_e32 v56, v60, v61
	v_cvt_pk_bf16_f32 v50, v92, v93
	v_cvt_pk_bf16_f32 v51, v94, v95
	global_store_dwordx4 v[88:89], v[48:51], off offset:256
	v_add_f32_e32 v58, v62, v63
	v_mul_f32_e32 v103, v60, v60
	v_pk_mul_f32 v[48:49], v[94:95], v[94:95]
	v_pk_mul_f32 v[50:51], v[92:93], v[92:93]
	v_mul_f32_e32 v61, v61, v61
	v_mul_f32_e32 v105, v62, v62
	v_mul_f32_e32 v63, v63, v63
	v_pk_mov_b32 v[88:89], v[50:51], v[48:49] op_sel:[1,0]
	v_mov_b32_e32 v51, v49
	v_mov_b32_e32 v102, v52
	v_mov_b32_e32 v60, v53
	v_mov_b32_e32 v104, v54
	v_mov_b32_e32 v62, v55
	v_add_f32_e32 v90, v84, v85
	v_add_f32_e32 v100, v86, v87
	v_mul_f32_e32 v107, v84, v84
	v_mul_f32_e32 v85, v85, v85
	v_mul_f32_e32 v109, v86, v86
	v_mul_f32_e32 v87, v87, v87
	v_mul_f32_e32 v57, v52, v52
	v_mul_f32_e32 v59, v53, v53
	v_pk_add_f32 v[48:49], v[88:89], v[50:51]
	v_pk_add_f32 v[50:51], v[102:103], v[60:61]
	v_pk_add_f32 v[52:53], v[104:105], v[62:63]
	v_mov_b32_e32 v106, v92
	v_mov_b32_e32 v84, v93
	v_mov_b32_e32 v108, v94
	v_mov_b32_e32 v86, v95
	v_mul_f32_e32 v91, v54, v54
	v_mul_f32_e32 v101, v55, v55
	v_pk_add_f32 v[50:51], v[50:51], v[52:53]
	v_pk_add_f32 v[52:53], v[106:107], v[84:85]
	v_pk_add_f32 v[54:55], v[108:109], v[86:87]
	v_pk_add_f32 v[48:49], v[48:49], v[48:49] op_sel_hi:[0,1]
	v_pk_add_f32 v[52:53], v[52:53], v[54:55]
	v_pk_add_f32 v[54:55], v[90:91], v[100:101]
	v_pk_add_f32 v[50:51], v[50:51], v[52:53]
	v_pk_add_f32 v[52:53], v[56:57], v[58:59]
	v_mov_b32_e32 v147, v49
	v_pk_add_f32 v[52:53], v[52:53], v[54:55]
	s_nop 0
	v_pk_add_f32 v[48:49], v[52:53], v[146:147]
	s_nop 0
	v_pk_add_f32 v[48:49], v[50:51], v[48:49]
	ds_bpermute_b32 v50, v116, v48
	ds_bpermute_b32 v51, v116, v49
	s_waitcnt lgkmcnt(0)
	v_pk_add_f32 v[48:49], v[48:49], v[50:51]
	ds_bpermute_b32 v50, v117, v48
	ds_bpermute_b32 v51, v117, v49
	s_and_saveexec_b64 s[56:57], s[38:39]
	s_cbranch_execz .LBB0_593
	v_lshlrev_b64 v[52:53], 7, v[82:83]
	s_waitcnt lgkmcnt(0)
	v_pk_add_f32 v[48:49], v[48:49], v[50:51]
	v_lshl_add_u64 v[50:51], s[12:13], 0, v[52:53]
	v_lshl_add_u64 v[50:51], s[54:55], 3, v[50:51]
	global_store_dwordx2 v[50:51], v[48:49], off
.LBB0_593:
	s_or_b64 exec, exec, s[56:57]
	v_lshlrev_b64 v[48:49], 11, v[80:81]
	v_lshl_add_u64 v[48:49], s[28:29], 0, v[48:49]
	v_lshl_add_u64 v[48:49], v[154:155], 1, v[48:49]
	v_pk_fma_f32 v[46:47], v[78:79], s[44:45], v[46:47] op_sel_hi:[1,0,1]
	v_pk_fma_f32 v[44:45], v[76:77], s[44:45], v[44:45] op_sel_hi:[1,0,1]
	s_waitcnt lgkmcnt(0)
	v_pk_fma_f32 v[50:51], v[74:75], s[44:45], v[42:43] op_sel_hi:[1,0,1]
	v_pk_fma_f32 v[52:53], v[72:73], s[44:45], v[40:41] op_sel_hi:[1,0,1]
	v_cvt_pk_bf16_f32 v40, v44, v45
	v_cvt_pk_bf16_f32 v41, v46, v47
	v_pk_fma_f32 v[38:39], v[70:71], s[44:45], v[38:39] op_sel_hi:[1,0,1]
	v_cvt_pk_bf16_f32 v42, v52, v53
	v_cvt_pk_bf16_f32 v43, v50, v51
	global_store_dwordx4 v[48:49], v[40:43], off
	v_pk_fma_f32 v[36:37], v[68:69], s[44:45], v[36:37] op_sel_hi:[1,0,1]
	v_pk_fma_f32 v[66:67], v[66:67], s[44:45], v[34:35] op_sel_hi:[1,0,1]
	v_pk_fma_f32 v[64:65], v[64:65], s[44:45], v[32:33] op_sel_hi:[1,0,1]
	v_cvt_pk_bf16_f32 v32, v36, v37
	v_cvt_pk_bf16_f32 v33, v38, v39
	v_add_f32_e32 v40, v44, v45
	v_cvt_pk_bf16_f32 v34, v64, v65
	v_cvt_pk_bf16_f32 v35, v66, v67
	global_store_dwordx4 v[48:49], v[32:35], off offset:256
	v_add_f32_e32 v42, v46, v47
	v_mul_f32_e32 v59, v44, v44
	v_pk_mul_f32 v[32:33], v[66:67], v[66:67]
	v_pk_mul_f32 v[34:35], v[64:65], v[64:65]
	v_mul_f32_e32 v45, v45, v45
	v_mul_f32_e32 v61, v46, v46
	v_mul_f32_e32 v47, v47, v47
	v_pk_mov_b32 v[48:49], v[34:35], v[32:33] op_sel:[1,0]
	v_mov_b32_e32 v35, v33
	v_mov_b32_e32 v58, v36
	v_mov_b32_e32 v44, v37
	v_mov_b32_e32 v60, v38
	v_mov_b32_e32 v46, v39
	v_add_f32_e32 v54, v52, v53
	v_add_f32_e32 v56, v50, v51
	v_mul_f32_e32 v63, v52, v52
	v_mul_f32_e32 v53, v53, v53
	v_mul_f32_e32 v73, v50, v50
	v_mul_f32_e32 v51, v51, v51
	v_mul_f32_e32 v41, v36, v36
	v_mul_f32_e32 v43, v37, v37
	v_pk_add_f32 v[32:33], v[48:49], v[34:35]
	v_pk_add_f32 v[34:35], v[58:59], v[44:45]
	v_pk_add_f32 v[36:37], v[60:61], v[46:47]
	v_mov_b32_e32 v62, v64
	v_mov_b32_e32 v52, v65
	v_mov_b32_e32 v72, v66
	v_mov_b32_e32 v50, v67
	v_mul_f32_e32 v55, v38, v38
	v_mul_f32_e32 v57, v39, v39
	v_pk_add_f32 v[34:35], v[34:35], v[36:37]
	v_pk_add_f32 v[36:37], v[62:63], v[52:53]
	v_pk_add_f32 v[38:39], v[72:73], v[50:51]
	v_pk_add_f32 v[32:33], v[32:33], v[32:33] op_sel_hi:[0,1]
	v_pk_add_f32 v[36:37], v[36:37], v[38:39]
	v_pk_add_f32 v[38:39], v[54:55], v[56:57]
	v_pk_add_f32 v[34:35], v[34:35], v[36:37]
	v_pk_add_f32 v[36:37], v[40:41], v[42:43]
	v_mov_b32_e32 v147, v33
	v_pk_add_f32 v[36:37], v[36:37], v[38:39]
	s_nop 0
	v_pk_add_f32 v[32:33], v[36:37], v[146:147]
	s_nop 0
	v_pk_add_f32 v[32:33], v[34:35], v[32:33]
	ds_bpermute_b32 v34, v116, v32
	ds_bpermute_b32 v35, v116, v33
	s_waitcnt lgkmcnt(0)
	v_pk_add_f32 v[32:33], v[32:33], v[34:35]
	ds_bpermute_b32 v34, v117, v32
	ds_bpermute_b32 v35, v117, v33
	s_and_saveexec_b64 s[56:57], s[38:39]
	s_cbranch_execz .LBB0_595
	v_lshlrev_b64 v[36:37], 7, v[80:81]
	s_waitcnt lgkmcnt(0)
	v_pk_add_f32 v[32:33], v[32:33], v[34:35]
	v_lshl_add_u64 v[34:35], s[12:13], 0, v[36:37]
	v_lshl_add_u64 v[34:35], s[54:55], 3, v[34:35]
	global_store_dwordx2 v[34:35], v[32:33], off
.LBB0_595:
	s_or_b64 exec, exec, s[56:57]
	v_add_u32_e32 v50, 0xa0, v156
	v_ashrrev_i32_e32 v51, 31, v50
	v_lshlrev_b64 v[32:33], 12, v[50:51]
	v_add_u32_e32 v48, 0xb0, v156
	v_lshl_add_u64 v[32:33], v[158:159], 0, v[32:33]
	v_ashrrev_i32_e32 v49, 31, v48
	s_waitcnt vmcnt(4)
	v_mov_b32_e32 v52, v214
	v_mov_b32_e32 v53, v215
	v_mov_b32_e32 v54, v216
	v_mov_b32_e32 v55, v217
	v_mov_b32_e32 v56, v218
	v_mov_b32_e32 v57, v219
	v_mov_b32_e32 v58, v220
	v_mov_b32_e32 v59, v221
	v_mov_b32_e32 v60, v222
	v_mov_b32_e32 v61, v223
	v_mov_b32_e32 v62, v224
	v_mov_b32_e32 v63, v225
	v_mov_b32_e32 v64, v226
	v_mov_b32_e32 v65, v227
	v_mov_b32_e32 v66, v228
	v_mov_b32_e32 v67, v229
	v_lshlrev_b64 v[32:33], 12, v[48:49]
	v_lshl_add_u64 v[36:37], v[158:159], 0, v[32:33]
	v_mov_b32_e32 v40, v230
	v_mov_b32_e32 v41, v231
	v_mov_b32_e32 v42, v232
	v_mov_b32_e32 v43, v233
	v_mov_b32_e32 v44, v234
	v_mov_b32_e32 v45, v235
	v_mov_b32_e32 v46, v236
	v_mov_b32_e32 v47, v237
	s_waitcnt lgkmcnt(0)
	v_mov_b32_e32 v32, v238
	v_mov_b32_e32 v33, v239
	v_mov_b32_e32 v34, v240
	v_mov_b32_e32 v35, v241
	s_nop 0
	v_mov_b32_e32 v36, v242
	v_mov_b32_e32 v37, v243
	v_mov_b32_e32 v38, v244
	v_mov_b32_e32 v39, v245
	v_lshlrev_b64 v[68:69], 11, v[50:51]
	v_pk_fma_f32 v[28:29], v[56:57], s[44:45], v[28:29] op_sel_hi:[1,0,1]
	v_lshl_add_u64 v[56:57], s[28:29], 0, v[68:69]
	v_lshl_add_u64 v[56:57], v[154:155], 1, v[56:57]
	v_pk_fma_f32 v[30:31], v[58:59], s[44:45], v[30:31] op_sel_hi:[1,0,1]
	v_pk_fma_f32 v[54:55], v[54:55], s[44:45], v[26:27] op_sel_hi:[1,0,1]
	v_pk_fma_f32 v[52:53], v[52:53], s[44:45], v[24:25] op_sel_hi:[1,0,1]
	v_cvt_pk_bf16_f32 v24, v28, v29
	v_cvt_pk_bf16_f32 v25, v30, v31
	v_pk_fma_f32 v[22:23], v[66:67], s[44:45], v[22:23] op_sel_hi:[1,0,1]
	v_cvt_pk_bf16_f32 v26, v52, v53
	v_cvt_pk_bf16_f32 v27, v54, v55
	global_store_dwordx4 v[56:57], v[24:27], off
	v_pk_fma_f32 v[20:21], v[64:65], s[44:45], v[20:21] op_sel_hi:[1,0,1]
	v_pk_fma_f32 v[62:63], v[62:63], s[44:45], v[18:19] op_sel_hi:[1,0,1]
	v_pk_fma_f32 v[60:61], v[60:61], s[44:45], v[16:17] op_sel_hi:[1,0,1]
	v_cvt_pk_bf16_f32 v16, v20, v21
	v_cvt_pk_bf16_f32 v17, v22, v23
	v_add_f32_e32 v24, v28, v29
	v_cvt_pk_bf16_f32 v18, v60, v61
	v_cvt_pk_bf16_f32 v19, v62, v63
	global_store_dwordx4 v[56:57], v[16:19], off offset:256
	v_add_f32_e32 v26, v30, v31
	v_mul_f32_e32 v71, v28, v28
	v_pk_mul_f32 v[16:17], v[62:63], v[62:63]
	v_pk_mul_f32 v[18:19], v[60:61], v[60:61]
	v_mul_f32_e32 v29, v29, v29
	v_mul_f32_e32 v73, v30, v30
	v_mul_f32_e32 v31, v31, v31
	v_pk_mov_b32 v[56:57], v[18:19], v[16:17] op_sel:[1,0]
	v_mov_b32_e32 v19, v17
	v_mov_b32_e32 v70, v20
	v_mov_b32_e32 v28, v21
	v_mov_b32_e32 v72, v22
	v_mov_b32_e32 v30, v23
	v_add_f32_e32 v58, v52, v53
	v_add_f32_e32 v68, v54, v55
	v_mul_f32_e32 v75, v52, v52
	v_mul_f32_e32 v53, v53, v53
	v_mul_f32_e32 v77, v54, v54
	v_mul_f32_e32 v55, v55, v55
	v_mul_f32_e32 v25, v20, v20
	v_mul_f32_e32 v27, v21, v21
	v_pk_add_f32 v[16:17], v[56:57], v[18:19]
	v_pk_add_f32 v[18:19], v[70:71], v[28:29]
	v_pk_add_f32 v[20:21], v[72:73], v[30:31]
	v_mov_b32_e32 v74, v60
	v_mov_b32_e32 v52, v61
	v_mov_b32_e32 v76, v62
	v_mov_b32_e32 v54, v63
	v_mul_f32_e32 v59, v22, v22
	v_mul_f32_e32 v69, v23, v23
	v_pk_add_f32 v[18:19], v[18:19], v[20:21]
	v_pk_add_f32 v[20:21], v[74:75], v[52:53]
	v_pk_add_f32 v[22:23], v[76:77], v[54:55]
	v_pk_add_f32 v[16:17], v[16:17], v[16:17] op_sel_hi:[0,1]
	v_pk_add_f32 v[20:21], v[20:21], v[22:23]
	v_pk_add_f32 v[22:23], v[58:59], v[68:69]
	v_pk_add_f32 v[18:19], v[18:19], v[20:21]
	v_pk_add_f32 v[20:21], v[24:25], v[26:27]
	v_mov_b32_e32 v147, v17
	v_pk_add_f32 v[20:21], v[20:21], v[22:23]
	s_nop 0
	v_pk_add_f32 v[16:17], v[20:21], v[146:147]
	s_nop 0
	v_pk_add_f32 v[16:17], v[18:19], v[16:17]
	ds_bpermute_b32 v18, v116, v16
	ds_bpermute_b32 v19, v116, v17
	s_waitcnt lgkmcnt(0)
	v_pk_add_f32 v[16:17], v[16:17], v[18:19]
	ds_bpermute_b32 v18, v117, v16
	ds_bpermute_b32 v19, v117, v17
	s_and_saveexec_b64 s[56:57], s[38:39]
	s_cbranch_execz .LBB0_597
	v_lshlrev_b64 v[20:21], 7, v[50:51]
	s_waitcnt lgkmcnt(0)
	v_pk_add_f32 v[16:17], v[16:17], v[18:19]
	v_lshl_add_u64 v[18:19], s[12:13], 0, v[20:21]
	v_lshl_add_u64 v[18:19], s[54:55], 3, v[18:19]
	global_store_dwordx2 v[18:19], v[16:17], off
.LBB0_597:
	s_or_b64 exec, exec, s[56:57]
	v_lshlrev_b64 v[16:17], 11, v[48:49]
	v_lshl_add_u64 v[16:17], s[28:29], 0, v[16:17]
	v_lshl_add_u64 v[16:17], v[154:155], 1, v[16:17]
	v_pk_fma_f32 v[14:15], v[46:47], s[44:45], v[14:15] op_sel_hi:[1,0,1]
	v_pk_fma_f32 v[12:13], v[44:45], s[44:45], v[12:13] op_sel_hi:[1,0,1]
	s_waitcnt lgkmcnt(0)
	v_pk_fma_f32 v[18:19], v[42:43], s[44:45], v[10:11] op_sel_hi:[1,0,1]
	v_pk_fma_f32 v[20:21], v[40:41], s[44:45], v[8:9] op_sel_hi:[1,0,1]
	v_cvt_pk_bf16_f32 v8, v12, v13
	v_cvt_pk_bf16_f32 v9, v14, v15
	v_pk_fma_f32 v[6:7], v[38:39], s[44:45], v[6:7] op_sel_hi:[1,0,1]
	v_cvt_pk_bf16_f32 v10, v20, v21
	v_cvt_pk_bf16_f32 v11, v18, v19
	global_store_dwordx4 v[16:17], v[8:11], off
	v_pk_fma_f32 v[4:5], v[36:37], s[44:45], v[4:5] op_sel_hi:[1,0,1]
	v_pk_fma_f32 v[34:35], v[34:35], s[44:45], v[2:3] op_sel_hi:[1,0,1]
	v_pk_fma_f32 v[32:33], v[32:33], s[44:45], v[0:1] op_sel_hi:[1,0,1]
	v_cvt_pk_bf16_f32 v0, v4, v5
	v_cvt_pk_bf16_f32 v1, v6, v7
	v_add_f32_e32 v8, v12, v13
	v_cvt_pk_bf16_f32 v2, v32, v33
	v_cvt_pk_bf16_f32 v3, v34, v35
	global_store_dwordx4 v[16:17], v[0:3], off offset:256
	v_add_f32_e32 v10, v14, v15
	v_mul_f32_e32 v27, v12, v12
	v_pk_mul_f32 v[0:1], v[34:35], v[34:35]
	v_pk_mul_f32 v[2:3], v[32:33], v[32:33]
	v_mul_f32_e32 v13, v13, v13
	v_mul_f32_e32 v29, v14, v14
	v_mul_f32_e32 v15, v15, v15
	v_pk_mov_b32 v[16:17], v[2:3], v[0:1] op_sel:[1,0]
	v_mov_b32_e32 v3, v1
	v_mov_b32_e32 v26, v4
	v_mov_b32_e32 v12, v5
	v_mov_b32_e32 v28, v6
	v_mov_b32_e32 v14, v7
	v_add_f32_e32 v22, v20, v21
	v_add_f32_e32 v24, v18, v19
	v_mul_f32_e32 v31, v20, v20
	v_mul_f32_e32 v21, v21, v21
	v_mul_f32_e32 v41, v18, v18
	v_mul_f32_e32 v19, v19, v19
	v_mul_f32_e32 v9, v4, v4
	v_mul_f32_e32 v11, v5, v5
	v_pk_add_f32 v[0:1], v[16:17], v[2:3]
	v_pk_add_f32 v[2:3], v[26:27], v[12:13]
	v_pk_add_f32 v[4:5], v[28:29], v[14:15]
	v_mov_b32_e32 v30, v32
	v_mov_b32_e32 v20, v33
	v_mov_b32_e32 v40, v34
	v_mov_b32_e32 v18, v35
	v_mul_f32_e32 v23, v6, v6
	v_mul_f32_e32 v25, v7, v7
	v_pk_add_f32 v[2:3], v[2:3], v[4:5]
	v_pk_add_f32 v[4:5], v[30:31], v[20:21]
	v_pk_add_f32 v[6:7], v[40:41], v[18:19]
	v_pk_add_f32 v[0:1], v[0:1], v[0:1] op_sel_hi:[0,1]
	v_pk_add_f32 v[4:5], v[4:5], v[6:7]
	v_pk_add_f32 v[6:7], v[22:23], v[24:25]
	v_pk_add_f32 v[2:3], v[2:3], v[4:5]
	v_pk_add_f32 v[4:5], v[8:9], v[10:11]
	v_mov_b32_e32 v147, v1
	v_pk_add_f32 v[4:5], v[4:5], v[6:7]
	s_nop 0
	v_pk_add_f32 v[0:1], v[4:5], v[146:147]
	s_nop 0
	v_pk_add_f32 v[0:1], v[2:3], v[0:1]
	ds_bpermute_b32 v2, v116, v0
	ds_bpermute_b32 v3, v116, v1
	s_waitcnt lgkmcnt(0)
	v_pk_add_f32 v[0:1], v[0:1], v[2:3]
	ds_bpermute_b32 v2, v117, v0
	ds_bpermute_b32 v3, v117, v1
	s_and_saveexec_b64 s[56:57], s[38:39]
	s_cbranch_execz .LBB0_599
	v_lshlrev_b64 v[4:5], 7, v[48:49]
	s_waitcnt lgkmcnt(0)
	v_pk_add_f32 v[0:1], v[0:1], v[2:3]
	v_lshl_add_u64 v[2:3], s[12:13], 0, v[4:5]
	v_lshl_add_u64 v[2:3], s[54:55], 3, v[2:3]
	global_store_dwordx2 v[2:3], v[0:1], off
